# adds: first half-trip of every GEMM unit peeled with C=0 MFMAs (the 128 accumulator clears per unit removed), G1 and G2
# speedup vs baseline: 1.0151x; 1.0037x over previous
; #define PG8_STAGE(bufoff, gbase, voff) do { _Pragma("unroll") for (int _i = 0; _i < 2; ++_i) \
;         __builtin_amdgcn_global_load_lds((const unsigned*)((const char*)(gbase) + (voff)[_i]), (LAS unsigned*)(lds + (bufoff) + ldsw + _i * 8192), 16, 0, 0); } while (0)
; #define PG8_WAIT_V(n) asm volatile("s_waitcnt vmcnt(" #n ")" ::: "memory")
; #define PG8_WAIT_L(n) asm volatile("s_waitcnt lgkmcnt(" #n ")" ::: "memory")
; #define PG8_BAR __builtin_amdgcn_s_barrier()
; template <class Epi>
; __device__ __forceinline__ void gemm_phase(LAS unsigned char* lds, const Gemm g, const StaticOrder& S, const Epi& E, unsigned long long& sw_acc) {
;     ...
;     E.pre_finish(pre);
;     PG8_WAIT_L(0);
;     PG8_STAGE(PG8_SB(1, 0), cB + kstep, voffB); PG8_STAGE(PG8_SA(1, 0), cA + kstepA, voffA); PG8_STAGE(PG8_SB(1, 1), cB + hstepB + kstep, voffB);
;     PG8_WAIT_V(6); PG8_BAR;
;     ...
; #pragma unroll
;         for (int a = 0; a < 2; ++a)
; #pragma unroll
;             for (int b = 0; b < 2; ++b)
; #pragma unroll
;                 for (int m = 0; m < 4; ++m)
; #pragma unroll
;                     for (int n = 0; n < 2; ++n) acc[a][b][m][n] = (f32x4){0.f, 0.f, 0.f, 0.f};
;         cur = nxt; cA = nA; cB = nB; ++ui;
.LBB0_118:
	s_or_b64 exec, exec, s[6:7]
	s_and_saveexec_b64 s[6:7], s[18:19]
	v_add_u32_e32 v12, 0, v12
	v_add_u32_e32 v12, 0x20000, v12
	ds_write_b32 v12, v13
	s_or_b64 exec, exec, s[6:7]
	v_and_b32_e32 v13, 15, v2
	v_bfe_u32 v2, v2, 4, 2
	v_lshlrev_b32_e32 v12, 3, v2
	v_lshlrev_b32_e32 v2, 4, v2
	v_lshl_or_b32 v187, s10, 6, v13
	v_lshl_or_b32 v14, v13, 6, v2
	v_lshlrev_b32_e32 v13, 2, v13
	s_and_b32 s1, s1, 3
	s_lshl_b32 s6, s10, 13
	v_and_b32_e32 v15, 32, v13
	s_waitcnt lgkmcnt(0)
	s_add_i32 m0, s31, 0x18000
	v_lshl_add_u64 v[8:9], v[8:9], 0, s[16:17]
	v_bitop3_b32 v16, v14, s6, v15 bitop3:0xde
	s_lshl_b32 s6, s1, 12
	global_load_lds_dwordx4 v[8:9], off
	v_lshl_add_u64 v[8:9], v[10:11], 0, s[16:17]
	s_add_i32 m0, s31, 0x1a000
	s_add_i32 s36, s31, 0x8000
	s_add_i32 s37, s31, 0xa000
	v_bitop3_b32 v218, v14, s6, v15 bitop3:0xde
	v_add_u32_e32 v254, 0x10000, v218
	v_add_u32_e32 v255, 0x18000, v218
	global_load_lds_dwordx4 v[8:9], off
	v_lshl_add_u64 v[6:7], v[6:7], 0, s[16:17]
	s_mov_b32 m0, s36
	s_add_u32 s6, s4, 0x10080
	global_load_lds_dwordx4 v[6:7], off
	v_lshl_add_u64 v[4:5], v[4:5], 0, s[16:17]
	s_mov_b32 m0, s37
	s_addc_u32 s7, s5, 0
	global_load_lds_dwordx4 v[4:5], off
	s_add_i32 m0, s31, 0x1c000
	v_lshl_add_u64 v[4:5], s[6:7], 0, v[196:197]
	global_load_lds_dwordx4 v[4:5], off
	v_lshl_add_u64 v[4:5], s[6:7], 0, v[192:193]
	s_add_i32 m0, s31, 0x1e000
	v_readlane_b32 s6, v250, 4
	global_load_lds_dwordx4 v[4:5], off
	v_readlane_b32 s7, v250, 5
	v_and_b32_e32 v4, 1, v24
	s_cmpk_lt_u32 s0, 0x100
	v_lshl_add_u64 v[200:201], s[6:7], 0, v[2:3]
	v_lshlrev_b32_e32 v2, 14, v24
	v_and_b32_e32 v2, 0xffff8000, v2
	v_lshl_add_u32 v2, v23, 11, v2
	v_lshl_or_b32 v2, v4, 6, v2
	s_cselect_b64 s[54:55], -1, 0
	s_lshl_b32 s0, s10, 8
	v_lshl_add_u32 v202, v25, 1, v2
	v_lshlrev_b32_e32 v2, 14, v20
	s_add_i32 s0, s0, 0
	v_and_b32_e32 v2, 0xffff8000, v2
	s_waitcnt vmcnt(6)
	s_add_i32 s0, s0, 0x20000
	v_lshl_add_u32 v2, v21, 11, v2
	v_and_b32_e32 v4, 1, v20
	v_add_u32_e32 v219, s0, v13
	v_lshl_or_b32 v220, s1, 6, v12
	v_lshl_or_b32 v2, v4, 6, v2
	v_readlane_b32 s0, v251, 27
	v_mov_b32_e32 v203, v3
	v_lshl_add_u32 v204, v22, 1, v2
	v_mov_b32_e32 v205, v3
	s_mov_b32 s70, 0
	v_add_u32_e32 v221, 0, v16
	v_lshlrev_b32_e32 v222, 2, v12
	s_mov_b32 s68, s0
	v_readlane_b32 s69, v251, 25
	s_barrier
	v_readlane_b32 s1, v251, 28
	s_branch .LBB0_122
.LBB0_121:
	s_mov_b32 s68, s56
	s_mov_b32 s69, s58
	s_mov_b64 s[52:53], s[64:65]
	s_mov_b32 s70, s71
	s_andn2_b64 vcc, exec, s[60:61]
	s_mov_b64 s[4:5], s[62:63]
	s_cbranch_vccz .LBB0_378

; #define PG8_STAGE(bufoff, gbase, voff) do { _Pragma("unroll") for (int _i = 0; _i < 2; ++_i) \
;         __builtin_amdgcn_global_load_lds((const unsigned*)((const char*)(gbase) + (voff)[_i]), (LAS unsigned*)(lds + (bufoff) + ldsw + _i * 8192), 16, 0, 0); } while (0)
; #define PG8_LDA(dst, b, h) do { _Pragma("unroll") for (int m = 0; m < 4; ++m) _Pragma("unroll") for (int k = 0; k < 2; ++k) dst[m][k] = *(const LAS h8*)(lds + PG8_SA(b, h) + aoff + m * 2048 + k * 1024); } while (0)
; #define PG8_LDB(dst, b, h) do { _Pragma("unroll") for (int n = 0; n < 2; ++n) _Pragma("unroll") for (int k = 0; k < 2; ++k) dst[n][k] = *(const LAS h8*)(lds + PG8_SB(b, h) + boff + n * 2048 + k * 1024); } while (0)
; #define PG8_MMA(ai, bj, At, Bt) do { __builtin_amdgcn_s_setprio(1); _Pragma("unroll") for (int m = 0; m < 4; ++m) _Pragma("unroll") for (int n = 0; n < 2; ++n) _Pragma("unroll") for (int k = 0; k < 2; ++k) \
;         acc[ai][bj][m][n] = __builtin_amdgcn_mfma_f32_16x16x32_f16(Bt[n][k], At[m][k], acc[ai][bj][m][n], 0, 0, 0); __builtin_amdgcn_s_setprio(0); } while (0)
; #define PG8_WAIT_V(n) asm volatile("s_waitcnt vmcnt(" #n ")" ::: "memory")
; template <class Epi>
; __device__ __forceinline__ void gemm_phase(LAS unsigned char* lds, const Gemm g, const StaticOrder& S, const Epi& E, unsigned long long& sw_acc) {
;     ...
;         const char* nA = has_next ? (const char*)g.A + (size_t)nxt.pm * tstep : cA; const char* nB = has_next ? (const char*)g.Bt + (size_t)nxt.pn * tstep : cB;
;         for (int t = 0; t < nt; t += 2) {
;             const bool last = (t == nt - 2);
;             const char* a1 = cA + (size_t)(t + 1) * kstepA;
;             const char* a2 = last ? nA : cA + (size_t)(t + 2) * kstepA; const char* b2 = last ? nB : cB + (size_t)(t + 2) * kstep;
;             const char* a3 = a2 + kstepA; const char* b3 = b2 + kstep;
;             PG8_LDB(B0, 0, 0); PG8_LDB(B1, 0, 1); PG8_SCHED; PG8_LDA(At, 0, 0); PG8_STAGE(PG8_SA(1, 1), a1 + hstep, voffA);
;             PG8_WAIT_V(8); PG8_WAIT_L(0); PG8_BAR; PG8_MMA(0, 0, At, B0); PG8_MMA(0, 1, At, B1); PG8_BAR; PG8_SCHED;
;             PG8_LDA(At, 0, 1); PG8_STAGE(PG8_SB(0, 0), b2, voffB); PG8_STAGE(PG8_SB(0, 1), b2 + hstepB, voffB); PG8_STAGE(PG8_SA(0, 0), a2, voffA);
;             PG8_WAIT_V(8); PG8_WAIT_L(0); PG8_BAR; PG8_MMA(1, 0, At, B0); PG8_MMA(1, 1, At, B1); PG8_BAR; PG8_SCHED;
.Lg1z_peel:
	s_add_u32 s6, s52, s4
	s_addc_u32 s7, s53, s5
	s_add_u32 s28, s6, 0x40080
	s_addc_u32 s29, s7, 0
	s_add_u32 s6, s6, 0x100
	s_addc_u32 s7, s7, 0
	s_add_u32 s15, s72, s4
	s_addc_u32 s20, s73, s5
	s_add_i32 s21, 0, 0x10000
	s_cmpk_eq_i32 s4, 0x700
	s_cselect_b32 s19, s0, s7
	s_cselect_b32 s18, s1, s6
	s_cselect_b32 s7, s10, s20
	s_cselect_b32 s6, s11, s15
	s_add_i32 s15, 0, 0x14000
	ds_read_b128 v[136:139], v254
	ds_read_b128 v[140:143], v254 offset:1024
	ds_read_b128 v[144:147], v254 offset:2048
	ds_read_b128 v[148:151], v254 offset:3072
	ds_read_b128 v[152:155], v254 offset:16384
	ds_read_b128 v[156:159], v254 offset:17408
	ds_read_b128 v[160:163], v254 offset:18432
	ds_read_b128 v[164:167], v254 offset:19456
	s_add_i32 m0, s31, 0xc000
	ds_read_b128 v[168:171], v221
	ds_read_b128 v[172:175], v221 offset:1024
	ds_read_b128 v[176:179], v221 offset:2048
	ds_read_b128 v[206:209], v221 offset:3072
	ds_read_b128 v[224:227], v221 offset:4096
	ds_read_b128 v[228:231], v221 offset:5120
	ds_read_b128 v[232:235], v221 offset:6144
	ds_read_b128 v[236:239], v221 offset:7168
	global_load_lds_dwordx4 v202, s[28:29]
	s_add_i32 m0, s31, 0xe000
	s_nop 0
	global_load_lds_dwordx4 v204, s[28:29]
	s_waitcnt vmcnt(8)
	s_waitcnt lgkmcnt(0)
	s_barrier
	s_waitcnt lgkmcnt(0)
	v_mfma_f32_16x16x32_f16 v[128:131], v[136:139], v[168:171], 0
	v_mfma_f32_16x16x32_f16 v[124:127], v[144:147], v[168:171], 0
	v_mfma_f32_16x16x32_f16 v[120:123], v[136:139], v[176:179], 0
	v_mfma_f32_16x16x32_f16 v[116:119], v[144:147], v[176:179], 0
	v_mfma_f32_16x16x32_f16 v[112:115], v[136:139], v[224:227], 0
	v_mfma_f32_16x16x32_f16 v[108:111], v[144:147], v[224:227], 0
	v_mfma_f32_16x16x32_f16 v[104:107], v[136:139], v[232:235], 0
	v_mfma_f32_16x16x32_f16 v[100:103], v[144:147], v[232:235], 0
	v_mfma_f32_16x16x32_f16 v[128:131], v[140:143], v[172:175], v[128:131]
	v_mfma_f32_16x16x32_f16 v[124:127], v[148:151], v[172:175], v[124:127]
	v_mfma_f32_16x16x32_f16 v[120:123], v[140:143], v[206:209], v[120:123]
	v_mfma_f32_16x16x32_f16 v[116:119], v[148:151], v[206:209], v[116:119]
	v_mfma_f32_16x16x32_f16 v[112:115], v[140:143], v[228:231], v[112:115]
	v_mfma_f32_16x16x32_f16 v[108:111], v[148:151], v[228:231], v[108:111]
	v_mfma_f32_16x16x32_f16 v[104:107], v[140:143], v[236:239], v[104:107]
	v_mfma_f32_16x16x32_f16 v[100:103], v[148:151], v[236:239], v[100:103]
	v_mfma_f32_16x16x32_f16 v[96:99], v[152:155], v[168:171], 0
	v_mfma_f32_16x16x32_f16 v[92:95], v[160:163], v[168:171], 0
	v_mfma_f32_16x16x32_f16 v[88:91], v[152:155], v[176:179], 0
	v_mfma_f32_16x16x32_f16 v[84:87], v[160:163], v[176:179], 0
	v_mfma_f32_16x16x32_f16 v[80:83], v[152:155], v[224:227], 0
	v_mfma_f32_16x16x32_f16 v[76:79], v[160:163], v[224:227], 0
	v_mfma_f32_16x16x32_f16 v[72:75], v[152:155], v[232:235], 0
	v_mfma_f32_16x16x32_f16 v[68:71], v[160:163], v[232:235], 0
	v_mfma_f32_16x16x32_f16 v[96:99], v[156:159], v[172:175], v[96:99]
	v_mfma_f32_16x16x32_f16 v[92:95], v[164:167], v[172:175], v[92:95]
	v_mfma_f32_16x16x32_f16 v[88:91], v[156:159], v[206:209], v[88:91]
	v_mfma_f32_16x16x32_f16 v[84:87], v[164:167], v[206:209], v[84:87]
	v_mfma_f32_16x16x32_f16 v[80:83], v[156:159], v[228:231], v[80:83]
	v_mfma_f32_16x16x32_f16 v[76:79], v[164:167], v[228:231], v[76:79]
	v_mfma_f32_16x16x32_f16 v[72:75], v[156:159], v[236:239], v[72:75]
	v_mfma_f32_16x16x32_f16 v[68:71], v[164:167], v[236:239], v[68:71]
	s_barrier
	s_add_i32 s20, s21, s26
	s_mov_b32 m0, s20
	ds_read_b128 v[168:171], v221 offset:16384
	ds_read_b128 v[172:175], v221 offset:17408
	ds_read_b128 v[176:179], v221 offset:18432
	ds_read_b128 v[206:209], v221 offset:19456
	ds_read_b128 v[224:227], v221 offset:20480
	ds_read_b128 v[228:231], v221 offset:21504
	ds_read_b128 v[232:235], v221 offset:22528
	ds_read_b128 v[236:239], v221 offset:23552
	global_load_lds_dwordx4 v196, s[6:7]
	s_add_i32 m0, s20, 0x2000
	s_add_u32 s20, s6, 0x10000
	s_addc_u32 s21, s7, 0
	s_add_i32 s15, s15, s26
	global_load_lds_dwordx4 v192, s[6:7]
	s_mov_b32 m0, s15
	s_nop 0
	global_load_lds_dwordx4 v196, s[20:21]
	s_add_i32 m0, s15, 0x2000
	s_nop 0
	global_load_lds_dwordx4 v192, s[20:21]
	s_mov_b32 m0, s31
	s_nop 0
	global_load_lds_dwordx4 v198, s[18:19]
	s_mov_b32 m0, s33
	s_nop 0
	global_load_lds_dwordx4 v194, s[18:19]
	s_waitcnt vmcnt(8)
	s_waitcnt lgkmcnt(0)
	s_barrier
	s_waitcnt lgkmcnt(0)
	v_mfma_f32_16x16x32_f16 v[64:67], v[136:139], v[168:171], 0
	v_mfma_f32_16x16x32_f16 v[60:63], v[144:147], v[168:171], 0
	v_mfma_f32_16x16x32_f16 v[56:59], v[136:139], v[176:179], 0
	v_mfma_f32_16x16x32_f16 v[52:55], v[144:147], v[176:179], 0
	v_mfma_f32_16x16x32_f16 v[48:51], v[136:139], v[224:227], 0
	v_mfma_f32_16x16x32_f16 v[44:47], v[144:147], v[224:227], 0
	v_mfma_f32_16x16x32_f16 v[40:43], v[136:139], v[232:235], 0
	v_mfma_f32_16x16x32_f16 v[36:39], v[144:147], v[232:235], 0
	v_mfma_f32_16x16x32_f16 v[64:67], v[140:143], v[172:175], v[64:67]
	v_mfma_f32_16x16x32_f16 v[60:63], v[148:151], v[172:175], v[60:63]
	v_mfma_f32_16x16x32_f16 v[56:59], v[140:143], v[206:209], v[56:59]
	v_mfma_f32_16x16x32_f16 v[52:55], v[148:151], v[206:209], v[52:55]
	v_mfma_f32_16x16x32_f16 v[48:51], v[140:143], v[228:231], v[48:51]
	v_mfma_f32_16x16x32_f16 v[44:47], v[148:151], v[228:231], v[44:47]
	v_mfma_f32_16x16x32_f16 v[40:43], v[140:143], v[236:239], v[40:43]
	v_mfma_f32_16x16x32_f16 v[36:39], v[148:151], v[236:239], v[36:39]
	v_mfma_f32_16x16x32_f16 v[32:35], v[152:155], v[168:171], 0
	v_mfma_f32_16x16x32_f16 v[28:31], v[160:163], v[168:171], 0
	v_mfma_f32_16x16x32_f16 v[24:27], v[152:155], v[176:179], 0
	v_mfma_f32_16x16x32_f16 v[20:23], v[160:163], v[176:179], 0
	v_mfma_f32_16x16x32_f16 v[16:19], v[152:155], v[224:227], 0
	v_mfma_f32_16x16x32_f16 v[12:15], v[160:163], v[224:227], 0
	v_mfma_f32_16x16x32_f16 v[8:11], v[152:155], v[232:235], 0
	v_mfma_f32_16x16x32_f16 v[4:7], v[160:163], v[232:235], 0
	v_mfma_f32_16x16x32_f16 v[32:35], v[156:159], v[172:175], v[32:35]
	v_mfma_f32_16x16x32_f16 v[28:31], v[164:167], v[172:175], v[28:31]
	v_mfma_f32_16x16x32_f16 v[24:27], v[156:159], v[206:209], v[24:27]
	v_mfma_f32_16x16x32_f16 v[20:23], v[164:167], v[206:209], v[20:23]
	v_mfma_f32_16x16x32_f16 v[16:19], v[156:159], v[228:231], v[16:19]
	v_mfma_f32_16x16x32_f16 v[12:15], v[164:167], v[228:231], v[12:15]
	v_mfma_f32_16x16x32_f16 v[8:11], v[156:159], v[236:239], v[8:11]
	v_mfma_f32_16x16x32_f16 v[4:7], v[164:167], v[236:239], v[4:7]
	s_barrier
	s_branch .Lg1z_mid

; #define PG8_STAGE(bufoff, gbase, voff) do { _Pragma("unroll") for (int _i = 0; _i < 2; ++_i) \
;         __builtin_amdgcn_global_load_lds((const unsigned*)((const char*)(gbase) + (voff)[_i]), (LAS unsigned*)(lds + (bufoff) + ldsw + _i * 8192), 16, 0, 0); } while (0)
; #define PG8_LDA(dst, b, h) do { _Pragma("unroll") for (int m = 0; m < 4; ++m) _Pragma("unroll") for (int k = 0; k < 2; ++k) dst[m][k] = *(const LAS h8*)(lds + PG8_SA(b, h) + aoff + m * 2048 + k * 1024); } while (0)
; #define PG8_LDB(dst, b, h) do { _Pragma("unroll") for (int n = 0; n < 2; ++n) _Pragma("unroll") for (int k = 0; k < 2; ++k) dst[n][k] = *(const LAS h8*)(lds + PG8_SB(b, h) + boff + n * 2048 + k * 1024); } while (0)
; #define PG8_MMA(ai, bj, At, Bt) do { __builtin_amdgcn_s_setprio(1); _Pragma("unroll") for (int m = 0; m < 4; ++m) _Pragma("unroll") for (int n = 0; n < 2; ++n) _Pragma("unroll") for (int k = 0; k < 2; ++k) \
;         acc[ai][bj][m][n] = __builtin_amdgcn_mfma_f32_16x16x32_f16(Bt[n][k], At[m][k], acc[ai][bj][m][n], 0, 0, 0); __builtin_amdgcn_s_setprio(0); } while (0)
; #define PG8_WAIT_V(n) asm volatile("s_waitcnt vmcnt(" #n ")" ::: "memory")
; #define PG8_WAIT_L(n) asm volatile("s_waitcnt lgkmcnt(" #n ")" ::: "memory")
; #define PG8_BAR __builtin_amdgcn_s_barrier()
; #define PG8_SCHED __builtin_amdgcn_sched_barrier(0)
; template <class Epi>
; __device__ __forceinline__ void gemm_phase(LAS unsigned char* lds, const Gemm g, const StaticOrder& S, const Epi& E, unsigned long long& sw_acc) {
;     ...
;             PG8_LDB(B0, 1, 0); PG8_LDB(B1, 1, 1); PG8_SCHED; PG8_LDA(At, 1, 0); PG8_STAGE(PG8_SA(0, 1), a2 + hstep, voffA);
;             PG8_WAIT_V(8); PG8_WAIT_L(0); PG8_BAR; PG8_MMA(0, 0, At, B0); PG8_MMA(0, 1, At, B1); PG8_BAR; PG8_SCHED;
;             PG8_LDA(At, 1, 1); PG8_STAGE(PG8_SB(1, 0), b3, voffB); PG8_STAGE(PG8_SB(1, 1), b3 + hstepB, voffB); PG8_STAGE(PG8_SA(1, 0), a3, voffA);
;             PG8_WAIT_V(8); PG8_WAIT_L(0); PG8_BAR; PG8_MMA(1, 0, At, B0); PG8_MMA(1, 1, At, B1); PG8_BAR; PG8_SCHED;
;         }
;         if (wr == 0) PG8_BAR;
.Lg1z_mid:
	s_add_i32 s15, 0, 0x18000
	s_add_i32 s20, 0, 0x1c000
	ds_read_b128 v[136:139], v255
	ds_read_b128 v[140:143], v255 offset:1024
	ds_read_b128 v[144:147], v255 offset:2048
	ds_read_b128 v[148:151], v255 offset:3072
	ds_read_b128 v[152:155], v255 offset:16384
	ds_read_b128 v[156:159], v255 offset:17408
	ds_read_b128 v[160:163], v255 offset:18432
	ds_read_b128 v[164:167], v255 offset:19456
	s_add_u32 s18, s18, 0x40000
	s_addc_u32 s19, s19, 0
	s_mov_b32 m0, s34
	ds_read_b128 v[168:171], v221 offset:32768
	ds_read_b128 v[172:175], v221 offset:33792
	ds_read_b128 v[176:179], v221 offset:34816
	ds_read_b128 v[206:209], v221 offset:35840
	ds_read_b128 v[224:227], v221 offset:36864
	ds_read_b128 v[228:231], v221 offset:37888
	ds_read_b128 v[232:235], v221 offset:38912
	ds_read_b128 v[236:239], v221 offset:39936
	global_load_lds_dwordx4 v198, s[18:19]
	s_mov_b32 m0, s35
	s_nop 0
	global_load_lds_dwordx4 v194, s[18:19]
	s_waitcnt vmcnt(8)
	s_waitcnt lgkmcnt(0)
	s_barrier
	s_waitcnt lgkmcnt(0)
	v_mfma_f32_16x16x32_f16 v[128:131], v[136:139], v[168:171], v[128:131]
	v_mfma_f32_16x16x32_f16 v[124:127], v[144:147], v[168:171], v[124:127]
	v_mfma_f32_16x16x32_f16 v[120:123], v[136:139], v[176:179], v[120:123]
	v_mfma_f32_16x16x32_f16 v[116:119], v[144:147], v[176:179], v[116:119]
	v_mfma_f32_16x16x32_f16 v[112:115], v[136:139], v[224:227], v[112:115]
	v_mfma_f32_16x16x32_f16 v[108:111], v[144:147], v[224:227], v[108:111]
	v_mfma_f32_16x16x32_f16 v[104:107], v[136:139], v[232:235], v[104:107]
	v_mfma_f32_16x16x32_f16 v[100:103], v[144:147], v[232:235], v[100:103]
	v_mfma_f32_16x16x32_f16 v[128:131], v[140:143], v[172:175], v[128:131]
	v_mfma_f32_16x16x32_f16 v[124:127], v[148:151], v[172:175], v[124:127]
	v_mfma_f32_16x16x32_f16 v[120:123], v[140:143], v[206:209], v[120:123]
	v_mfma_f32_16x16x32_f16 v[116:119], v[148:151], v[206:209], v[116:119]
	v_mfma_f32_16x16x32_f16 v[112:115], v[140:143], v[228:231], v[112:115]
	v_mfma_f32_16x16x32_f16 v[108:111], v[148:151], v[228:231], v[108:111]
	v_mfma_f32_16x16x32_f16 v[104:107], v[140:143], v[236:239], v[104:107]
	v_mfma_f32_16x16x32_f16 v[100:103], v[148:151], v[236:239], v[100:103]
	v_mfma_f32_16x16x32_f16 v[96:99], v[152:155], v[168:171], v[96:99]
	v_mfma_f32_16x16x32_f16 v[92:95], v[160:163], v[168:171], v[92:95]
	v_mfma_f32_16x16x32_f16 v[88:91], v[152:155], v[176:179], v[88:91]
	v_mfma_f32_16x16x32_f16 v[84:87], v[160:163], v[176:179], v[84:87]
	v_mfma_f32_16x16x32_f16 v[80:83], v[152:155], v[224:227], v[80:83]
	v_mfma_f32_16x16x32_f16 v[76:79], v[160:163], v[224:227], v[76:79]
	v_mfma_f32_16x16x32_f16 v[72:75], v[152:155], v[232:235], v[72:75]
	v_mfma_f32_16x16x32_f16 v[68:71], v[160:163], v[232:235], v[68:71]
	v_mfma_f32_16x16x32_f16 v[96:99], v[156:159], v[172:175], v[96:99]
	v_mfma_f32_16x16x32_f16 v[92:95], v[164:167], v[172:175], v[92:95]
	v_mfma_f32_16x16x32_f16 v[88:91], v[156:159], v[206:209], v[88:91]
	v_mfma_f32_16x16x32_f16 v[84:87], v[164:167], v[206:209], v[84:87]
	v_mfma_f32_16x16x32_f16 v[80:83], v[156:159], v[228:231], v[80:83]
	v_mfma_f32_16x16x32_f16 v[76:79], v[164:167], v[228:231], v[76:79]
	v_mfma_f32_16x16x32_f16 v[72:75], v[156:159], v[236:239], v[72:75]
	v_mfma_f32_16x16x32_f16 v[68:71], v[164:167], v[236:239], v[68:71]
	s_barrier
	s_add_i32 s15, s15, s26
	s_add_u32 s28, s6, 0x80
	s_addc_u32 s29, s7, 0
	s_mov_b32 m0, s15
	ds_read_b128 v[168:171], v221 offset:49152
	ds_read_b128 v[172:175], v221 offset:50176
	ds_read_b128 v[176:179], v221 offset:51200
	ds_read_b128 v[206:209], v221 offset:52224
	ds_read_b128 v[224:227], v221 offset:53248
	ds_read_b128 v[228:231], v221 offset:54272
	ds_read_b128 v[232:235], v221 offset:55296
	ds_read_b128 v[236:239], v221 offset:56320
	global_load_lds_dwordx4 v196, s[28:29]
	s_add_i32 m0, s15, 0x2000
	s_add_u32 s6, s6, 0x10080
	s_addc_u32 s7, s7, 0
	s_add_i32 s15, s20, s26
	global_load_lds_dwordx4 v192, s[28:29]
	s_mov_b32 m0, s15
	s_sub_u32 s18, s18, 0x3ff80
	s_subb_u32 s19, s19, 0
	global_load_lds_dwordx4 v196, s[6:7]
	s_add_i32 m0, s15, 0x2000
	s_nop 0
	global_load_lds_dwordx4 v192, s[6:7]
	s_mov_b32 m0, s36
	s_nop 0
	global_load_lds_dwordx4 v198, s[18:19]
	s_mov_b32 m0, s37
	s_nop 0
	global_load_lds_dwordx4 v194, s[18:19]
	s_waitcnt vmcnt(8)
	s_waitcnt lgkmcnt(0)
	s_barrier
	s_waitcnt lgkmcnt(0)
	v_mfma_f32_16x16x32_f16 v[64:67], v[136:139], v[168:171], v[64:67]
	v_mfma_f32_16x16x32_f16 v[60:63], v[144:147], v[168:171], v[60:63]
	v_mfma_f32_16x16x32_f16 v[56:59], v[136:139], v[176:179], v[56:59]
	v_mfma_f32_16x16x32_f16 v[52:55], v[144:147], v[176:179], v[52:55]
	v_mfma_f32_16x16x32_f16 v[48:51], v[136:139], v[224:227], v[48:51]
	v_mfma_f32_16x16x32_f16 v[44:47], v[144:147], v[224:227], v[44:47]
	v_mfma_f32_16x16x32_f16 v[40:43], v[136:139], v[232:235], v[40:43]
	v_mfma_f32_16x16x32_f16 v[36:39], v[144:147], v[232:235], v[36:39]
	v_mfma_f32_16x16x32_f16 v[64:67], v[140:143], v[172:175], v[64:67]
	v_mfma_f32_16x16x32_f16 v[60:63], v[148:151], v[172:175], v[60:63]
	v_mfma_f32_16x16x32_f16 v[56:59], v[140:143], v[206:209], v[56:59]
	v_mfma_f32_16x16x32_f16 v[52:55], v[148:151], v[206:209], v[52:55]
	v_mfma_f32_16x16x32_f16 v[48:51], v[140:143], v[228:231], v[48:51]
	v_mfma_f32_16x16x32_f16 v[44:47], v[148:151], v[228:231], v[44:47]
	v_mfma_f32_16x16x32_f16 v[40:43], v[140:143], v[236:239], v[40:43]
	v_mfma_f32_16x16x32_f16 v[36:39], v[148:151], v[236:239], v[36:39]
	v_mfma_f32_16x16x32_f16 v[32:35], v[152:155], v[168:171], v[32:35]
	v_mfma_f32_16x16x32_f16 v[28:31], v[160:163], v[168:171], v[28:31]
	v_mfma_f32_16x16x32_f16 v[24:27], v[152:155], v[176:179], v[24:27]
	v_mfma_f32_16x16x32_f16 v[20:23], v[160:163], v[176:179], v[20:23]
	v_mfma_f32_16x16x32_f16 v[16:19], v[152:155], v[224:227], v[16:19]
	v_mfma_f32_16x16x32_f16 v[12:15], v[160:163], v[224:227], v[12:15]
	v_mfma_f32_16x16x32_f16 v[8:11], v[152:155], v[232:235], v[8:11]
	v_mfma_f32_16x16x32_f16 v[4:7], v[160:163], v[232:235], v[4:7]
	v_mfma_f32_16x16x32_f16 v[32:35], v[156:159], v[172:175], v[32:35]
	v_mfma_f32_16x16x32_f16 v[28:31], v[164:167], v[172:175], v[28:31]
	v_mfma_f32_16x16x32_f16 v[24:27], v[156:159], v[206:209], v[24:27]
	v_mfma_f32_16x16x32_f16 v[20:23], v[164:167], v[206:209], v[20:23]
	v_mfma_f32_16x16x32_f16 v[16:19], v[156:159], v[228:231], v[16:19]
	v_mfma_f32_16x16x32_f16 v[12:15], v[164:167], v[228:231], v[12:15]
	v_mfma_f32_16x16x32_f16 v[8:11], v[156:159], v[236:239], v[8:11]
	v_mfma_f32_16x16x32_f16 v[4:7], v[164:167], v[236:239], v[4:7]
	s_barrier
	s_add_i32 s14, s14, 2
	s_add_u32 s4, s4, 0x100
	s_addc_u32 s5, s5, 0
	s_cmp_gt_u32 s14, 13
	s_cbranch_scc0 .LBB0_134
	s_and_b64 vcc, exec, s[54:55]
	s_cbranch_vccz .LBB0_137
	s_barrier

; template <class Epi>
; __device__ __forceinline__ void gemm_phase(LAS unsigned char* lds, const Gemm g, const StaticOrder& S, const Epi& E, unsigned long long& sw_acc) {
;     ...
;         const bool has_next = S.next(ui + 1, nxt);
;         const char* nA = has_next ? (const char*)g.A + (size_t)nxt.pm * tstep : cA; const char* nB = has_next ? (const char*)g.Bt + (size_t)nxt.pn * tstep : cB;
;     ...
; #pragma unroll
;         for (int a = 0; a < 2; ++a)
; #pragma unroll
;             for (int b = 0; b < 2; ++b)
; #pragma unroll
;                 for (int m = 0; m < 4; ++m)
; #pragma unroll
;                     for (int n = 0; n < 2; ++n) acc[a][b][m][n] = (f32x4){0.f, 0.f, 0.f, 0.f};
;         cur = nxt; cA = nA; cB = nB; ++ui;
.LBB0_699:
	s_mov_b32 s50, s10
	s_ashr_i32 s51, s10, 31
	s_lshl_b64 s[10:11], s[50:51], 19
	s_add_u32 s56, s33, s10
	s_addc_u32 s57, s26, s11
	s_mov_b32 s52, s5
	s_and_b64 s[10:11], s[54:55], exec
	s_cselect_b32 s1, s57, s19
	s_cselect_b32 s5, s56, s18
	s_ashr_i32 s53, s52, 31
	s_lshl_b64 s[10:11], s[52:53], 19
	s_add_u32 s58, s27, s10
	s_addc_u32 s59, s28, s11
	s_and_b64 s[10:11], s[54:55], exec
	s_cselect_b32 s10, s59, s7
	s_cselect_b32 s11, s58, s6
	s_add_u32 s14, s6, 0x100
	s_addc_u32 s15, s7, 0
	s_add_u32 s6, s18, 0x41000
	s_addc_u32 s7, s19, 0
	s_mov_b32 s22, -2
	s_waitcnt vmcnt(0)
; #define PG8_STAGE(bufoff, gbase, voff) do { _Pragma("unroll") for (int _i = 0; _i < 2; ++_i) \
;         __builtin_amdgcn_global_load_lds((const unsigned*)((const char*)(gbase) + (voff)[_i]), (LAS unsigned*)(lds + (bufoff) + ldsw + _i * 8192), 16, 0, 0); } while (0)
; #define PG8_LDA(dst, b, h) do { _Pragma("unroll") for (int m = 0; m < 4; ++m) _Pragma("unroll") for (int k = 0; k < 2; ++k) dst[m][k] = *(const LAS h8*)(lds + PG8_SA(b, h) + aoff + m * 2048 + k * 1024); } while (0)
; #define PG8_LDB(dst, b, h) do { _Pragma("unroll") for (int n = 0; n < 2; ++n) _Pragma("unroll") for (int k = 0; k < 2; ++k) dst[n][k] = *(const LAS h8*)(lds + PG8_SB(b, h) + boff + n * 2048 + k * 1024); } while (0)
; #define PG8_MMA(ai, bj, At, Bt) do { __builtin_amdgcn_s_setprio(1); _Pragma("unroll") for (int m = 0; m < 4; ++m) _Pragma("unroll") for (int n = 0; n < 2; ++n) _Pragma("unroll") for (int k = 0; k < 2; ++k) \
;         acc[ai][bj][m][n] = __builtin_amdgcn_mfma_f32_16x16x32_f16(Bt[n][k], At[m][k], acc[ai][bj][m][n], 0, 0, 0); __builtin_amdgcn_s_setprio(0); } while (0)
; #define PG8_WAIT_V(n) asm volatile("s_waitcnt vmcnt(" #n ")" ::: "memory")
; template <class Epi>
; __device__ __forceinline__ void gemm_phase(LAS unsigned char* lds, const Gemm g, const StaticOrder& S, const Epi& E, unsigned long long& sw_acc) {
;     ...
;             const char* a1 = cA + (size_t)(t + 1) * kstepA;
;             const char* a2 = last ? nA : cA + (size_t)(t + 2) * kstepA; const char* b2 = last ? nB : cB + (size_t)(t + 2) * kstep;
;             const char* a3 = a2 + kstepA; const char* b3 = b2 + kstep;
;             PG8_LDB(B0, 0, 0); PG8_LDB(B1, 0, 1); PG8_SCHED; PG8_LDA(At, 0, 0); PG8_STAGE(PG8_SA(1, 1), a1 + hstep, voffA);
;             PG8_WAIT_V(8); PG8_WAIT_L(0); PG8_BAR; PG8_MMA(0, 0, At, B0); PG8_MMA(0, 1, At, B1); PG8_BAR; PG8_SCHED;
;             PG8_LDA(At, 0, 1); PG8_STAGE(PG8_SB(0, 0), b2, voffB); PG8_STAGE(PG8_SB(0, 1), b2 + hstepB, voffB); PG8_STAGE(PG8_SA(0, 0), a2, voffA);
;             PG8_WAIT_V(8); PG8_WAIT_L(0); PG8_BAR; PG8_MMA(1, 0, At, B0); PG8_MMA(1, 1, At, B1); PG8_BAR; PG8_SCHED;
;     ...
; #pragma unroll
;         for (int a = 0; a < 2; ++a)
; #pragma unroll
;             for (int b = 0; b < 2; ++b)
; #pragma unroll
;                 for (int m = 0; m < 4; ++m)
; #pragma unroll
;                     for (int n = 0; n < 2; ++n) acc[a][b][m][n] = (f32x4){0.f, 0.f, 0.f, 0.f};
.Lg2z_peel:
	s_add_u32 s18, s6, 0xfffc1000
	s_addc_u32 s19, s7, -1
	s_cmp_eq_u32 s22, 12
	s_cselect_b32 s24, s5, s18
	s_cselect_b32 s25, s1, s19
	s_cselect_b32 s20, s11, s14
	s_cselect_b32 s21, s10, s15
	s_add_u32 s18, s24, 0x1000
	s_addc_u32 s19, s25, 0
	s_add_i32 s23, 0, 0x10000
	s_add_i32 s42, 0, 0x14000
	v_add_u32_e32 v144, s23, v200
	v_add_u32_e32 v170, s42, v200
	ds_read_b128 v[124:127], v144
	ds_read_b128 v[136:139], v144 offset:1024
	ds_read_b128 v[140:143], v144 offset:2048
	ds_read_b128 v[144:147], v144 offset:3072
	ds_read_b128 v[148:151], v170
	ds_read_b128 v[152:155], v170 offset:1024
	ds_read_b128 v[156:159], v170 offset:2048
	ds_read_b128 v[170:173], v170 offset:3072
	v_lshl_add_u64 v[178:179], s[6:7], 0, v[166:167]
	s_add_i32 m0, s30, 0xc000
	ds_read_b128 v[174:177], v202
	ds_read_b128 v[192:195], v202 offset:1024
	ds_read_b128 v[196:199], v202 offset:2048
	ds_read_b128 v[204:207], v202 offset:3072
	ds_read_b128 v[218:221], v202 offset:4096
	ds_read_b128 v[222:225], v202 offset:5120
	ds_read_b128 v[226:229], v202 offset:6144
	ds_read_b128 v[230:233], v202 offset:7168
	global_load_lds_dwordx4 v[178:179], off
	v_lshl_add_u64 v[178:179], s[6:7], 0, v[168:169]
	s_add_i32 m0, s30, 0xe000
	s_nop 0
	global_load_lds_dwordx4 v[178:179], off
	s_waitcnt vmcnt(8)
	s_waitcnt lgkmcnt(0)
	s_barrier
	s_waitcnt lgkmcnt(0)
	v_mfma_f32_16x16x32_f16 v[132:135], v[124:127], v[174:177], 0
	v_mfma_f32_16x16x32_f16 v[128:131], v[140:143], v[174:177], 0
	v_mfma_f32_16x16x32_f16 v[112:115], v[124:127], v[196:199], 0
	v_mfma_f32_16x16x32_f16 v[108:111], v[140:143], v[196:199], 0
	v_mfma_f32_16x16x32_f16 v[96:99], v[124:127], v[218:221], 0
	v_mfma_f32_16x16x32_f16 v[92:95], v[140:143], v[218:221], 0
	v_mfma_f32_16x16x32_f16 v[80:83], v[124:127], v[226:229], 0
	v_mfma_f32_16x16x32_f16 v[76:79], v[140:143], v[226:229], 0
	v_mfma_f32_16x16x32_f16 v[132:135], v[136:139], v[192:195], v[132:135]
	v_mfma_f32_16x16x32_f16 v[128:131], v[144:147], v[192:195], v[128:131]
	v_mfma_f32_16x16x32_f16 v[112:115], v[136:139], v[204:207], v[112:115]
	v_mfma_f32_16x16x32_f16 v[108:111], v[144:147], v[204:207], v[108:111]
	v_mfma_f32_16x16x32_f16 v[96:99], v[136:139], v[222:225], v[96:99]
	v_mfma_f32_16x16x32_f16 v[92:95], v[144:147], v[222:225], v[92:95]
	v_mfma_f32_16x16x32_f16 v[80:83], v[136:139], v[230:233], v[80:83]
	v_mfma_f32_16x16x32_f16 v[76:79], v[144:147], v[230:233], v[76:79]
	v_mfma_f32_16x16x32_f16 v[120:123], v[148:151], v[174:177], 0
	v_mfma_f32_16x16x32_f16 v[116:119], v[156:159], v[174:177], 0
	v_mfma_f32_16x16x32_f16 v[104:107], v[148:151], v[196:199], 0
	v_mfma_f32_16x16x32_f16 v[100:103], v[156:159], v[196:199], 0
	v_mfma_f32_16x16x32_f16 v[88:91], v[148:151], v[218:221], 0
	v_mfma_f32_16x16x32_f16 v[84:87], v[156:159], v[218:221], 0
	v_mfma_f32_16x16x32_f16 v[72:75], v[148:151], v[226:229], 0
	v_mfma_f32_16x16x32_f16 v[68:71], v[156:159], v[226:229], 0
	v_mfma_f32_16x16x32_f16 v[120:123], v[152:155], v[192:195], v[120:123]
	v_mfma_f32_16x16x32_f16 v[116:119], v[170:173], v[192:195], v[116:119]
	v_mfma_f32_16x16x32_f16 v[104:107], v[152:155], v[204:207], v[104:107]
	v_mfma_f32_16x16x32_f16 v[100:103], v[170:173], v[204:207], v[100:103]
	v_mfma_f32_16x16x32_f16 v[88:91], v[152:155], v[222:225], v[88:91]
	v_mfma_f32_16x16x32_f16 v[84:87], v[170:173], v[222:225], v[84:87]
	v_mfma_f32_16x16x32_f16 v[72:75], v[152:155], v[230:233], v[72:75]
	v_mfma_f32_16x16x32_f16 v[68:71], v[170:173], v[230:233], v[68:71]
	s_barrier
	s_add_i32 s23, s23, s29
	v_lshl_add_u64 v[178:179], s[20:21], 0, v[2:3]
	s_mov_b32 m0, s23
	ds_read_b128 v[174:177], v202 offset:16384
	ds_read_b128 v[192:195], v202 offset:17408
	ds_read_b128 v[196:199], v202 offset:18432
	ds_read_b128 v[204:207], v202 offset:19456
	ds_read_b128 v[218:221], v202 offset:20480
	ds_read_b128 v[222:225], v202 offset:21504
	ds_read_b128 v[226:229], v202 offset:22528
	ds_read_b128 v[230:233], v202 offset:23552
	global_load_lds_dwordx4 v[178:179], off
	s_add_i32 m0, s23, 0x2000
	s_add_u32 s40, s20, 0x10000
	v_lshl_add_u64 v[208:209], s[20:21], 0, v[160:161]
	s_addc_u32 s41, s21, 0
	s_add_i32 s23, s42, s29
	global_load_lds_dwordx4 v[208:209], off
	v_lshl_add_u64 v[234:235], s[40:41], 0, v[2:3]
	s_mov_b32 m0, s23
	s_nop 0
	global_load_lds_dwordx4 v[234:235], off
	v_lshl_add_u64 v[234:235], s[40:41], 0, v[160:161]
	s_add_i32 m0, s23, 0x2000
	s_nop 0
	global_load_lds_dwordx4 v[234:235], off
	v_lshl_add_u64 v[234:235], s[24:25], 0, v[164:165]
	s_mov_b32 m0, s30
	s_nop 0
	global_load_lds_dwordx4 v[234:235], off
	v_lshl_add_u64 v[234:235], s[24:25], 0, v[162:163]
	s_mov_b32 m0, s31
	s_nop 0
	global_load_lds_dwordx4 v[234:235], off
	s_waitcnt vmcnt(8)
	s_waitcnt lgkmcnt(0)
	s_barrier
	s_waitcnt lgkmcnt(0)
	v_mfma_f32_16x16x32_f16 v[64:67], v[124:127], v[174:177], 0
	v_mfma_f32_16x16x32_f16 v[60:63], v[140:143], v[174:177], 0
	v_mfma_f32_16x16x32_f16 v[48:51], v[124:127], v[196:199], 0
	v_mfma_f32_16x16x32_f16 v[44:47], v[140:143], v[196:199], 0
	v_mfma_f32_16x16x32_f16 v[32:35], v[124:127], v[218:221], 0
	v_mfma_f32_16x16x32_f16 v[28:31], v[140:143], v[218:221], 0
	v_mfma_f32_16x16x32_f16 v[16:19], v[124:127], v[226:229], 0
	v_mfma_f32_16x16x32_f16 v[12:15], v[140:143], v[226:229], 0
	v_mfma_f32_16x16x32_f16 v[64:67], v[136:139], v[192:195], v[64:67]
	v_mfma_f32_16x16x32_f16 v[60:63], v[144:147], v[192:195], v[60:63]
	v_mfma_f32_16x16x32_f16 v[48:51], v[136:139], v[204:207], v[48:51]
	v_mfma_f32_16x16x32_f16 v[44:47], v[144:147], v[204:207], v[44:47]
	v_mfma_f32_16x16x32_f16 v[32:35], v[136:139], v[222:225], v[32:35]
	v_mfma_f32_16x16x32_f16 v[28:31], v[144:147], v[222:225], v[28:31]
	v_mfma_f32_16x16x32_f16 v[16:19], v[136:139], v[230:233], v[16:19]
	v_mfma_f32_16x16x32_f16 v[12:15], v[144:147], v[230:233], v[12:15]
	v_mfma_f32_16x16x32_f16 v[56:59], v[148:151], v[174:177], 0
	v_mfma_f32_16x16x32_f16 v[52:55], v[156:159], v[174:177], 0
	v_mfma_f32_16x16x32_f16 v[40:43], v[148:151], v[196:199], 0
	v_mfma_f32_16x16x32_f16 v[36:39], v[156:159], v[196:199], 0
	v_mfma_f32_16x16x32_f16 v[24:27], v[148:151], v[218:221], 0
	v_mfma_f32_16x16x32_f16 v[20:23], v[156:159], v[218:221], 0
	v_mfma_f32_16x16x32_f16 v[8:11], v[148:151], v[226:229], 0
	v_mfma_f32_16x16x32_f16 v[4:7], v[156:159], v[226:229], 0
	v_mfma_f32_16x16x32_f16 v[56:59], v[152:155], v[192:195], v[56:59]
	v_mfma_f32_16x16x32_f16 v[52:55], v[170:173], v[192:195], v[52:55]
	v_mfma_f32_16x16x32_f16 v[40:43], v[152:155], v[204:207], v[40:43]
	v_mfma_f32_16x16x32_f16 v[36:39], v[170:173], v[204:207], v[36:39]
	v_mfma_f32_16x16x32_f16 v[24:27], v[152:155], v[222:225], v[24:27]
	v_mfma_f32_16x16x32_f16 v[20:23], v[170:173], v[222:225], v[20:23]
	v_mfma_f32_16x16x32_f16 v[8:11], v[152:155], v[230:233], v[8:11]
	v_mfma_f32_16x16x32_f16 v[4:7], v[170:173], v[230:233], v[4:7]
	s_barrier
	s_branch .Lg2z_mid

; #define PG8_STAGE(bufoff, gbase, voff) do { _Pragma("unroll") for (int _i = 0; _i < 2; ++_i) \
;         __builtin_amdgcn_global_load_lds((const unsigned*)((const char*)(gbase) + (voff)[_i]), (LAS unsigned*)(lds + (bufoff) + ldsw + _i * 8192), 16, 0, 0); } while (0)
; #define PG8_LDA(dst, b, h) do { _Pragma("unroll") for (int m = 0; m < 4; ++m) _Pragma("unroll") for (int k = 0; k < 2; ++k) dst[m][k] = *(const LAS h8*)(lds + PG8_SA(b, h) + aoff + m * 2048 + k * 1024); } while (0)
; #define PG8_LDB(dst, b, h) do { _Pragma("unroll") for (int n = 0; n < 2; ++n) _Pragma("unroll") for (int k = 0; k < 2; ++k) dst[n][k] = *(const LAS h8*)(lds + PG8_SB(b, h) + boff + n * 2048 + k * 1024); } while (0)
; #define PG8_MMA(ai, bj, At, Bt) do { __builtin_amdgcn_s_setprio(1); _Pragma("unroll") for (int m = 0; m < 4; ++m) _Pragma("unroll") for (int n = 0; n < 2; ++n) _Pragma("unroll") for (int k = 0; k < 2; ++k) \
;         acc[ai][bj][m][n] = __builtin_amdgcn_mfma_f32_16x16x32_f16(Bt[n][k], At[m][k], acc[ai][bj][m][n], 0, 0, 0); __builtin_amdgcn_s_setprio(0); } while (0)
; #define PG8_WAIT_V(n) asm volatile("s_waitcnt vmcnt(" #n ")" ::: "memory")
; #define PG8_WAIT_L(n) asm volatile("s_waitcnt lgkmcnt(" #n ")" ::: "memory")
; #define PG8_BAR __builtin_amdgcn_s_barrier()
; #define PG8_SCHED __builtin_amdgcn_sched_barrier(0)
; template <class Epi>
; __device__ __forceinline__ void gemm_phase(LAS unsigned char* lds, const Gemm g, const StaticOrder& S, const Epi& E, unsigned long long& sw_acc) {
;     ...
;             PG8_LDB(B0, 1, 0); PG8_LDB(B1, 1, 1); PG8_SCHED; PG8_LDA(At, 1, 0); PG8_STAGE(PG8_SA(0, 1), a2 + hstep, voffA);
;             PG8_WAIT_V(8); PG8_WAIT_L(0); PG8_BAR; PG8_MMA(0, 0, At, B0); PG8_MMA(0, 1, At, B1); PG8_BAR; PG8_SCHED;
.Lg2z_mid:
	s_add_i32 s23, 0, 0x18000
	s_add_i32 s40, 0, 0x1c000
	v_add_u32_e32 v144, s23, v200
	v_add_u32_e32 v170, s40, v200
	ds_read_b128 v[124:127], v144
	ds_read_b128 v[136:139], v144 offset:1024
	ds_read_b128 v[140:143], v144 offset:2048
	ds_read_b128 v[144:147], v144 offset:3072
	ds_read_b128 v[148:151], v170
	ds_read_b128 v[152:155], v170 offset:1024
	ds_read_b128 v[156:159], v170 offset:2048
	ds_read_b128 v[170:173], v170 offset:3072
	s_add_u32 s24, s24, 0x40000
	s_addc_u32 s25, s25, 0
	s_mov_b32 m0, s34
	v_lshl_add_u64 v[234:235], s[24:25], 0, v[164:165]
	ds_read_b128 v[174:177], v202 offset:32768
	ds_read_b128 v[192:195], v202 offset:33792
	ds_read_b128 v[196:199], v202 offset:34816
	ds_read_b128 v[204:207], v202 offset:35840
	ds_read_b128 v[218:221], v202 offset:36864
	ds_read_b128 v[222:225], v202 offset:37888
	ds_read_b128 v[226:229], v202 offset:38912
	ds_read_b128 v[230:233], v202 offset:39936
	global_load_lds_dwordx4 v[234:235], off
	v_lshl_add_u64 v[234:235], s[24:25], 0, v[162:163]
	s_mov_b32 m0, s35
	s_nop 0
	global_load_lds_dwordx4 v[234:235], off
	s_waitcnt vmcnt(8)
	s_waitcnt lgkmcnt(0)
	s_barrier
	s_waitcnt lgkmcnt(0)
	v_mfma_f32_16x16x32_f16 v[132:135], v[124:127], v[174:177], v[132:135]
	v_mfma_f32_16x16x32_f16 v[128:131], v[140:143], v[174:177], v[128:131]
	v_mfma_f32_16x16x32_f16 v[112:115], v[124:127], v[196:199], v[112:115]
	v_mfma_f32_16x16x32_f16 v[108:111], v[140:143], v[196:199], v[108:111]
	v_mfma_f32_16x16x32_f16 v[96:99], v[124:127], v[218:221], v[96:99]
	v_mfma_f32_16x16x32_f16 v[92:95], v[140:143], v[218:221], v[92:95]
	v_mfma_f32_16x16x32_f16 v[80:83], v[124:127], v[226:229], v[80:83]
	v_mfma_f32_16x16x32_f16 v[76:79], v[140:143], v[226:229], v[76:79]
	v_mfma_f32_16x16x32_f16 v[132:135], v[136:139], v[192:195], v[132:135]
	v_mfma_f32_16x16x32_f16 v[128:131], v[144:147], v[192:195], v[128:131]
	v_mfma_f32_16x16x32_f16 v[112:115], v[136:139], v[204:207], v[112:115]
	v_mfma_f32_16x16x32_f16 v[108:111], v[144:147], v[204:207], v[108:111]
	v_mfma_f32_16x16x32_f16 v[96:99], v[136:139], v[222:225], v[96:99]
	v_mfma_f32_16x16x32_f16 v[92:95], v[144:147], v[222:225], v[92:95]
	v_mfma_f32_16x16x32_f16 v[80:83], v[136:139], v[230:233], v[80:83]
	v_mfma_f32_16x16x32_f16 v[76:79], v[144:147], v[230:233], v[76:79]
	v_mfma_f32_16x16x32_f16 v[120:123], v[148:151], v[174:177], v[120:123]
	v_mfma_f32_16x16x32_f16 v[116:119], v[156:159], v[174:177], v[116:119]
	v_mfma_f32_16x16x32_f16 v[104:107], v[148:151], v[196:199], v[104:107]
	v_mfma_f32_16x16x32_f16 v[100:103], v[156:159], v[196:199], v[100:103]
	v_mfma_f32_16x16x32_f16 v[88:91], v[148:151], v[218:221], v[88:91]
	v_mfma_f32_16x16x32_f16 v[84:87], v[156:159], v[218:221], v[84:87]
	v_mfma_f32_16x16x32_f16 v[72:75], v[148:151], v[226:229], v[72:75]
	v_mfma_f32_16x16x32_f16 v[68:71], v[156:159], v[226:229], v[68:71]
	v_mfma_f32_16x16x32_f16 v[120:123], v[152:155], v[192:195], v[120:123]
	v_mfma_f32_16x16x32_f16 v[116:119], v[170:173], v[192:195], v[116:119]
	v_mfma_f32_16x16x32_f16 v[104:107], v[152:155], v[204:207], v[104:107]
	v_mfma_f32_16x16x32_f16 v[100:103], v[170:173], v[204:207], v[100:103]
	v_mfma_f32_16x16x32_f16 v[88:91], v[152:155], v[222:225], v[88:91]
	v_mfma_f32_16x16x32_f16 v[84:87], v[170:173], v[222:225], v[84:87]
	v_mfma_f32_16x16x32_f16 v[72:75], v[152:155], v[230:233], v[72:75]
	v_mfma_f32_16x16x32_f16 v[68:71], v[170:173], v[230:233], v[68:71]
	s_barrier
; #define PG8_STAGE(bufoff, gbase, voff) do { _Pragma("unroll") for (int _i = 0; _i < 2; ++_i) \
;         __builtin_amdgcn_global_load_lds((const unsigned*)((const char*)(gbase) + (voff)[_i]), (LAS unsigned*)(lds + (bufoff) + ldsw + _i * 8192), 16, 0, 0); } while (0)
; #define PG8_LDA(dst, b, h) do { _Pragma("unroll") for (int m = 0; m < 4; ++m) _Pragma("unroll") for (int k = 0; k < 2; ++k) dst[m][k] = *(const LAS h8*)(lds + PG8_SA(b, h) + aoff + m * 2048 + k * 1024); } while (0)
; #define PG8_MMA(ai, bj, At, Bt) do { __builtin_amdgcn_s_setprio(1); _Pragma("unroll") for (int m = 0; m < 4; ++m) _Pragma("unroll") for (int n = 0; n < 2; ++n) _Pragma("unroll") for (int k = 0; k < 2; ++k) \
;         acc[ai][bj][m][n] = __builtin_amdgcn_mfma_f32_16x16x32_f16(Bt[n][k], At[m][k], acc[ai][bj][m][n], 0, 0, 0); __builtin_amdgcn_s_setprio(0); } while (0)
; #define PG8_WAIT_V(n) asm volatile("s_waitcnt vmcnt(" #n ")" ::: "memory")
; #define PG8_WAIT_L(n) asm volatile("s_waitcnt lgkmcnt(" #n ")" ::: "memory")
; #define PG8_BAR __builtin_amdgcn_s_barrier()
; #define PG8_SCHED __builtin_amdgcn_sched_barrier(0)
; template <class Epi>
; __device__ __forceinline__ void gemm_phase(LAS unsigned char* lds, const Gemm g, const StaticOrder& S, const Epi& E, unsigned long long& sw_acc) {
;     ...
;             PG8_LDA(At, 1, 1); PG8_STAGE(PG8_SB(1, 0), b3, voffB); PG8_STAGE(PG8_SB(1, 1), b3 + hstepB, voffB); PG8_STAGE(PG8_SA(1, 0), a3, voffA);
;             PG8_WAIT_V(8); PG8_WAIT_L(0); PG8_BAR; PG8_MMA(1, 0, At, B0); PG8_MMA(1, 1, At, B1); PG8_BAR; PG8_SCHED;
;         }
;         if (wr == 0) PG8_BAR;
	s_add_i32 s23, s23, s29
	v_lshl_add_u64 v[178:179], v[178:179], 0, s[16:17]
	s_mov_b32 m0, s23
	ds_read_b128 v[174:177], v202 offset:49152
	ds_read_b128 v[192:195], v202 offset:50176
	ds_read_b128 v[196:199], v202 offset:51200
	ds_read_b128 v[204:207], v202 offset:52224
	ds_read_b128 v[218:221], v202 offset:53248
	ds_read_b128 v[222:225], v202 offset:54272
	ds_read_b128 v[226:229], v202 offset:55296
	ds_read_b128 v[230:233], v202 offset:56320
	global_load_lds_dwordx4 v[178:179], off
	s_add_i32 m0, s23, 0x2000
	s_add_u32 s20, s20, 0x10080
	v_lshl_add_u64 v[178:179], v[208:209], 0, s[16:17]
	s_addc_u32 s21, s21, 0
	s_add_i32 s23, s40, s29
	global_load_lds_dwordx4 v[178:179], off
	v_lshl_add_u64 v[178:179], s[20:21], 0, v[2:3]
	s_mov_b32 m0, s23
	s_nop 0
	global_load_lds_dwordx4 v[178:179], off
	v_lshl_add_u64 v[178:179], s[20:21], 0, v[160:161]
	s_add_i32 m0, s23, 0x2000
	s_nop 0
	global_load_lds_dwordx4 v[178:179], off
	v_lshl_add_u64 v[178:179], s[18:19], 0, v[164:165]
	s_mov_b32 m0, s37
	s_nop 0
	global_load_lds_dwordx4 v[178:179], off
	v_lshl_add_u64 v[178:179], s[18:19], 0, v[162:163]
	s_mov_b32 m0, s60
	s_nop 0
	global_load_lds_dwordx4 v[178:179], off
	s_waitcnt vmcnt(8)
	s_waitcnt lgkmcnt(0)
	s_barrier
	s_waitcnt lgkmcnt(0)
	v_mfma_f32_16x16x32_f16 v[64:67], v[124:127], v[174:177], v[64:67]
	v_mfma_f32_16x16x32_f16 v[60:63], v[140:143], v[174:177], v[60:63]
	v_mfma_f32_16x16x32_f16 v[48:51], v[124:127], v[196:199], v[48:51]
	v_mfma_f32_16x16x32_f16 v[44:47], v[140:143], v[196:199], v[44:47]
	v_mfma_f32_16x16x32_f16 v[32:35], v[124:127], v[218:221], v[32:35]
	v_mfma_f32_16x16x32_f16 v[28:31], v[140:143], v[218:221], v[28:31]
	v_mfma_f32_16x16x32_f16 v[16:19], v[124:127], v[226:229], v[16:19]
	v_mfma_f32_16x16x32_f16 v[12:15], v[140:143], v[226:229], v[12:15]
	v_mfma_f32_16x16x32_f16 v[64:67], v[136:139], v[192:195], v[64:67]
	v_mfma_f32_16x16x32_f16 v[60:63], v[144:147], v[192:195], v[60:63]
	v_mfma_f32_16x16x32_f16 v[48:51], v[136:139], v[204:207], v[48:51]
	v_mfma_f32_16x16x32_f16 v[44:47], v[144:147], v[204:207], v[44:47]
	v_mfma_f32_16x16x32_f16 v[32:35], v[136:139], v[222:225], v[32:35]
	v_mfma_f32_16x16x32_f16 v[28:31], v[144:147], v[222:225], v[28:31]
	v_mfma_f32_16x16x32_f16 v[16:19], v[136:139], v[230:233], v[16:19]
	v_mfma_f32_16x16x32_f16 v[12:15], v[144:147], v[230:233], v[12:15]
	v_mfma_f32_16x16x32_f16 v[56:59], v[148:151], v[174:177], v[56:59]
	v_mfma_f32_16x16x32_f16 v[52:55], v[156:159], v[174:177], v[52:55]
	v_mfma_f32_16x16x32_f16 v[40:43], v[148:151], v[196:199], v[40:43]
	v_mfma_f32_16x16x32_f16 v[36:39], v[156:159], v[196:199], v[36:39]
	v_mfma_f32_16x16x32_f16 v[24:27], v[148:151], v[218:221], v[24:27]
	v_mfma_f32_16x16x32_f16 v[20:23], v[156:159], v[218:221], v[20:23]
	v_mfma_f32_16x16x32_f16 v[8:11], v[148:151], v[226:229], v[8:11]
	v_mfma_f32_16x16x32_f16 v[4:7], v[156:159], v[226:229], v[4:7]
	v_mfma_f32_16x16x32_f16 v[56:59], v[152:155], v[192:195], v[56:59]
	v_mfma_f32_16x16x32_f16 v[52:55], v[170:173], v[192:195], v[52:55]
	v_mfma_f32_16x16x32_f16 v[40:43], v[152:155], v[204:207], v[40:43]
	v_mfma_f32_16x16x32_f16 v[36:39], v[170:173], v[204:207], v[36:39]
	v_mfma_f32_16x16x32_f16 v[24:27], v[152:155], v[222:225], v[24:27]
	v_mfma_f32_16x16x32_f16 v[20:23], v[170:173], v[222:225], v[20:23]
	v_mfma_f32_16x16x32_f16 v[8:11], v[152:155], v[230:233], v[8:11]
	v_mfma_f32_16x16x32_f16 v[4:7], v[170:173], v[230:233], v[4:7]
	s_barrier
	s_add_i32 s22, s22, 2
	s_add_u32 s14, s14, 0x100
	s_addc_u32 s15, s15, 0
	s_add_u32 s6, s6, 0x2000
	s_addc_u32 s7, s7, 0
	s_cmp_gt_u32 s22, 13
	s_cbranch_scc0 .LBB0_700
	s_and_b64 vcc, exec, s[46:47]
	s_cbranch_vccz .LBB0_703
	s_barrier
